# ml_state_pass: K^T/V^T chunk loads issued two chunks ahead into two alternating register sets (counted vmcnt per wave class)
# speedup vs baseline: 1.0022x; 1.0022x over previous
.LBB0_442:
	s_or_b64 exec, exec, s[34:35]
	v_add_u32_e32 v21, 0, v73
	v_add_u32_e32 v38, 0, v81
	s_waitcnt vmcnt(4)
	ds_write_b128 v21, v[0:3] offset:4096
	s_waitcnt vmcnt(3)
	ds_write_b128 v38, v[4:7] offset:4096
	v_add_u32_e32 v38, 0, v82
	s_waitcnt vmcnt(2)
	ds_write_b128 v38, v[8:11] offset:4096
	v_add_u32_e32 v38, 0, v83
	s_waitcnt vmcnt(1)
	ds_write_b128 v38, v[12:15] offset:4096
	s_waitcnt vmcnt(0)
	ds_write_b128 v21, v[16:19] offset:38912
	s_and_saveexec_b64 s[18:19], s[2:3]
	ds_write_b32 v74, v88 offset:47616
	s_or_b64 exec, exec, s[18:19]
	v_lshl_add_u64 v[50:51], v[22:23], 0, v[160:161]
	v_and_b32_e32 v22, 64, v227
	v_add_u32_e32 v21, -1, v227
	v_cmp_lt_i32_e32 vcc, v21, v22
	s_mov_b32 s24, 0x8800
	v_mad_i64_i32 v[38:39], s[18:19], v24, s24, 0
	v_cndmask_b32_e32 v21, v21, v227, vcc
	v_lshlrev_b32_e32 v89, 2, v21
	v_add_u32_e32 v21, -2, v227
	v_cmp_lt_i32_e32 vcc, v21, v22
	v_mad_i64_i32 v[40:41], s[18:19], v25, s24, 0
	s_nop 0
	v_cndmask_b32_e32 v21, v21, v227, vcc
	v_lshlrev_b32_e32 v90, 2, v21
	v_add_u32_e32 v21, -4, v227
	v_cmp_lt_i32_e32 vcc, v21, v22
	v_mad_i64_i32 v[42:43], s[18:19], v27, s24, 0
	s_nop 0
	v_cndmask_b32_e32 v21, v21, v227, vcc
	v_lshlrev_b32_e32 v91, 2, v21
	v_add_u32_e32 v21, -8, v227
	v_cmp_lt_i32_e32 vcc, v21, v22
	v_mad_i64_i32 v[44:45], s[18:19], v26, s24, 0
	s_nop 0
	v_cndmask_b32_e32 v21, v21, v227, vcc
	s_cmp_eq_u32 s36, 0
	v_lshlrev_b32_e32 v92, 2, v21
	v_add_u32_e32 v21, -16, v227
	s_cselect_b64 s[18:19], -1, 0
	v_cmp_lt_i32_e32 vcc, v21, v22
	s_lshl_b32 s53, s37, 12
	s_addk_i32 s53, 0xff00
	v_cndmask_b32_e32 v21, v21, v227, vcc
	v_lshlrev_b32_e32 v93, 2, v21
	v_subrev_u32_e32 v21, 32, v227
	s_cmp_eq_u32 s42, 0
	v_cmp_lt_i32_e32 vcc, v21, v22
	s_cselect_b64 s[44:45], -1, 0
	s_lshl_b32 s24, s36, 2
	v_cndmask_b32_e32 v21, v21, v227, vcc
	s_or_b32 s24, s24, s41
	v_lshlrev_b32_e32 v94, 2, v21
	v_bfrev_b32_e32 v21, 0.5
	s_and_b64 s[34:35], s[16:17], s[44:45]
	s_and_b64 s[36:37], s[44:45], s[12:13]
	v_xor_b32_e32 v23, 16, v227
	v_add_u32_e32 v22, 64, v22
	s_mul_i32 s24, s24, 0x11000
	v_lshl_or_b32 v95, v227, 2, v21
	v_ashrrev_i32_e32 v21, 31, v20
	v_cmp_lt_i32_e32 vcc, v23, v22
	s_add_u32 s56, s47, s24
	s_addc_u32 s57, s48, 0
	v_cndmask_b32_e32 v23, v227, v23, vcc
	v_lshl_add_u64 v[20:21], v[20:21], 2, s[28:29]
	s_lshl_b32 s24, s41, 2
	v_lshlrev_b32_e32 v98, 2, v23
	v_xor_b32_e32 v23, 32, v227
	v_lshl_add_u64 v[52:53], v[20:21], 0, s[24:25]
	s_mul_i32 s41, s40, 0x220000
	v_lshl_or_b32 v20, s42, 13, v85
	v_cmp_lt_i32_e32 vcc, v23, v22
	s_mul_hi_i32 s24, s40, 0x220000
	v_or_b32_e32 v54, s41, v20
	v_mov_b32_e32 v20, 0x4400
	v_cndmask_b32_e64 v46, v66, v49, s[18:19]
	v_cndmask_b32_e64 v48, v67, v68, s[18:19]
	s_mul_i32 s55, s40, 34
	v_cndmask_b32_e32 v22, v227, v23, vcc
	v_mov_b32_e32 v55, s24
	v_mad_i64_i32 v[58:59], s[40:41], s40, v20, v[36:37]
	v_mov_b32_e32 v20, 0
	s_mov_b32 s58, 0
	v_lshl_add_u32 v96, v46, 2, v47
	v_lshl_add_u32 v97, v48, 2, v47
	s_mov_b32 s54, 34
	v_lshlrev_b32_e32 v99, 2, v22
	v_lshl_add_u64 v[56:57], v[34:35], 0, v[54:55]
	v_lshlrev_b32_e32 v100, 2, v46
	v_lshlrev_b32_e32 v101, 2, v48
	v_mov_b32_e32 v21, v20
	v_mov_b32_e32 v22, v20
	v_mov_b32_e32 v23, v20
	v_mov_b32_e32 v24, v20
	v_mov_b32_e32 v25, v20
	v_mov_b32_e32 v26, v20
	v_mov_b32_e32 v27, v20
	v_mov_b32_e32 v105, v20
	v_mov_b32_e32 v106, v20
	v_mov_b32_e32 v107, v20
	v_mov_b32_e32 v108, v20
	v_mov_b32_e32 v104, v20
	v_mov_b32_e32 v103, v20
	v_mov_b32_e32 v102, v20
	v_mov_b32_e32 v60, v20
	v_mov_b32_e32 v61, v20
	s_mov_b32 s24, 1
	s_mov_b32 s44, 0
	s_and_b64 s[42:43], s[18:19], exec
	s_cselect_b32 s42, s24, s44
	s_lshl_b32 s43, s42, 7
	s_or_b32 s44, s43, s52
	s_add_i32 s43, s43, s53
	s_cmp_lt_u32 s42, 2
	s_cselect_b32 s42, s44, s43
	s_ashr_i32 s43, s42, 31
	s_lshl_b64 s[44:45], s[42:43], 1
	v_lshl_add_u64 v[128:129], v[30:31], 0, s[44:45]
	v_lshl_add_u64 v[120:121], v[128:129], 0, v[38:39]
	v_lshl_add_u64 v[124:125], v[128:129], 0, v[40:41]
	v_lshl_add_u64 v[130:131], v[128:129], 0, v[42:43]
	v_lshl_add_u64 v[132:133], v[128:129], 0, v[44:45]
	v_lshl_add_u64 v[136:137], v[50:51], 0, s[44:45]
	global_load_dwordx4 v[120:123], v[120:121], off
	s_nop 0
	global_load_dwordx4 v[124:127], v[124:125], off
	s_nop 0
	global_load_dwordx4 v[128:131], v[130:131], off
	s_nop 0
	global_load_dwordx4 v[132:135], v[132:133], off
	v_mov_b32_e32 v140, 0
	global_load_dwordx4 v[136:139], v[136:137], off
	s_and_saveexec_b64 s[44:45], s[2:3]
	s_cbranch_execz .Lmls_gpB
	v_or_b32_e32 v62, s42, v71
	s_movk_i32 s42, 0x140
	v_mad_i64_i32 v[62:63], s[42:43], v62, s42, v[52:53]
	global_load_dword v140, v[62:63], off offset:256
.Lmls_gpB:
	s_or_b64 exec, exec, s[44:45]
	s_waitcnt lgkmcnt(0)
	s_barrier
	s_branch .LBB0_447

.LBB0_447:
	s_add_i32 s24, s58, 1
	s_cmp_lg_u32 s58, 33
	s_cselect_b64 s[40:41], -1, 0
	s_cmp_gt_u32 s58, 31
	s_cbranch_scc1 .LBB0_451
	s_add_i32 s42, s24, 1
	s_add_i32 s43, s54, -1
	s_and_b64 s[44:45], s[18:19], exec
	s_cselect_b32 s42, s42, s43
	s_lshl_b32 s43, s42, 7
	s_or_b32 s44, s43, s52
	s_add_i32 s43, s43, s53
	s_cmp_lt_u32 s42, 2
	s_cselect_b32 s42, s44, s43
	s_ashr_i32 s43, s42, 31
	s_lshl_b64 s[44:45], s[42:43], 1
	s_bitcmp1_b32 s58, 0
	s_cbranch_scc1 .Lmls_topB
	v_lshl_add_u64 v[8:9], v[30:31], 0, s[44:45]
	v_lshl_add_u64 v[0:1], v[8:9], 0, v[38:39]
	v_lshl_add_u64 v[4:5], v[8:9], 0, v[40:41]
	v_lshl_add_u64 v[10:11], v[8:9], 0, v[42:43]
	v_lshl_add_u64 v[12:13], v[8:9], 0, v[44:45]
	v_lshl_add_u64 v[16:17], v[50:51], 0, s[44:45]
	global_load_dwordx4 v[0:3], v[0:1], off
	s_nop 0
	global_load_dwordx4 v[4:7], v[4:5], off
	s_nop 0
	global_load_dwordx4 v[8:11], v[10:11], off
	s_nop 0
	global_load_dwordx4 v[12:15], v[12:13], off
	v_mov_b32_e32 v88, 0
	global_load_dwordx4 v[16:19], v[16:17], off
	s_and_saveexec_b64 s[44:45], s[2:3]
	s_cbranch_execz .Lmls_gtA
	v_or_b32_e32 v62, s42, v71
	s_movk_i32 s42, 0x140
	v_mad_i64_i32 v[62:63], s[42:43], v62, s42, v[52:53]
	global_load_dword v88, v[62:63], off offset:256
.Lmls_gtA:
	s_or_b64 exec, exec, s[44:45]
	s_branch .LBB0_451
.Lmls_topB:
	v_lshl_add_u64 v[128:129], v[30:31], 0, s[44:45]
	v_lshl_add_u64 v[120:121], v[128:129], 0, v[38:39]
	v_lshl_add_u64 v[124:125], v[128:129], 0, v[40:41]
	v_lshl_add_u64 v[130:131], v[128:129], 0, v[42:43]
	v_lshl_add_u64 v[132:133], v[128:129], 0, v[44:45]
	v_lshl_add_u64 v[136:137], v[50:51], 0, s[44:45]
	global_load_dwordx4 v[120:123], v[120:121], off
	s_nop 0
	global_load_dwordx4 v[124:127], v[124:125], off
	s_nop 0
	global_load_dwordx4 v[128:131], v[130:131], off
	s_nop 0
	global_load_dwordx4 v[132:135], v[132:133], off
	v_mov_b32_e32 v140, 0
	global_load_dwordx4 v[136:139], v[136:137], off
	s_and_saveexec_b64 s[44:45], s[2:3]
	s_cbranch_execz .Lmls_gtB
	v_or_b32_e32 v62, s42, v71
	s_movk_i32 s42, 0x140
	v_mad_i64_i32 v[62:63], s[42:43], v62, s42, v[52:53]
	global_load_dword v140, v[62:63], off offset:256

.LBB0_456:
	s_or_b64 exec, exec, s[42:43]
	v_sub_f32_e32 v61, v61, v65
	v_mul_f32_e32 v61, 0x3fb8aa3b, v61
	v_exp_f32_e32 v64, v61
	v_cvt_pk_bf16_f32 v61, v20, v161
	global_store_short v[56:57], v61, off offset:-512
	v_cvt_pk_bf16_f32 v61, v105, v161
	global_store_short v[56:57], v61, off offset:-256
	v_cvt_pk_bf16_f32 v61, v106, v161
	global_store_short v[56:57], v61, off
	v_cvt_pk_bf16_f32 v61, v107, v161
	v_or_b32_e32 v106, 0x1000, v54
	v_mov_b32_e32 v107, v55
	global_store_short v[56:57], v61, off offset:256
	v_cvt_pk_bf16_f32 v61, v108, v161
	v_lshl_add_u64 v[106:107], v[32:33], 0, v[106:107]
	global_store_short v[106:107], v61, off
	v_cvt_pk_bf16_f32 v61, v104, v161
	v_or_b32_e32 v104, 0x1100, v54
	v_mov_b32_e32 v105, v55
	v_lshl_add_u64 v[104:105], v[32:33], 0, v[104:105]
	global_store_short v[104:105], v61, off
	v_or_b32_e32 v104, 0x1200, v54
	v_mov_b32_e32 v105, v55
	v_cvt_pk_bf16_f32 v61, v103, v161
	v_lshl_add_u64 v[104:105], v[32:33], 0, v[104:105]
	global_store_short v[104:105], v61, off
	v_cvt_pk_bf16_f32 v61, v102, v161
	v_or_b32_e32 v102, 0x1300, v54
	v_mov_b32_e32 v103, v55
	v_lshl_add_u64 v[102:103], v[32:33], 0, v[102:103]
	global_store_short v[102:103], v61, off
	s_waitcnt lgkmcnt(0)
	v_lshl_add_u32 v61, v75, 1, s44
	v_add_u32_e32 v62, v61, v77
	ds_read_b128 v[102:105], v76
	ds_read_b128 v[106:109], v76 offset:16
	s_waitcnt lgkmcnt(5)
	ds_read_b128 v[110:113], v62 offset:4096
	v_add_u32_e32 v61, v61, v84
	v_pk_mul_f32 v[22:23], v[22:23], v[64:65] op_sel_hi:[1,0]
	v_pk_mul_f32 v[20:21], v[20:21], v[64:65] op_sel_hi:[1,0]
	v_pk_mul_f32 v[26:27], v[26:27], v[64:65] op_sel_hi:[1,0]
	s_waitcnt lgkmcnt(0)
	v_lshlrev_b32_e32 v114, 16, v110
	v_and_b32_e32 v110, 0xffff0000, v110
	v_lshlrev_b32_e32 v115, 16, v111
	v_and_b32_e32 v111, 0xffff0000, v111
	v_lshlrev_b32_e32 v116, 16, v112
	v_and_b32_e32 v112, 0xffff0000, v112
	v_lshlrev_b32_e32 v117, 16, v113
	v_and_b32_e32 v113, 0xffff0000, v113
	v_mul_f32_e32 v102, v102, v114
	v_mul_f32_e32 v103, v103, v110
	v_mul_f32_e32 v104, v104, v115
	v_mul_f32_e32 v114, v106, v116
	v_fma_f32 v116, v106, v116, v102
	v_mul_f32_e32 v106, v107, v112
	v_fma_f32 v110, v107, v112, v103
	v_mul_f32_e32 v107, v108, v117
	v_fma_f32 v112, v108, v117, v104
	v_mul_f32_e32 v105, v105, v111
	v_mul_f32_e32 v108, v109, v113
	v_fma_f32 v111, v109, v113, v105
	v_cvt_pk_bf16_f32 v102, v102, v103
	v_cvt_pk_bf16_f32 v103, v104, v105
	v_cvt_pk_bf16_f32 v104, v114, v106
	v_cvt_pk_bf16_f32 v105, v107, v108
	ds_read_b128 v[106:109], v61 offset:38912
	s_waitcnt lgkmcnt(0)
	v_mfma_f32_16x16x32_bf16 v[20:23], v[106:109], v[102:105], v[20:23]
	ds_read_b128 v[106:109], v61 offset:43264
	v_pk_mul_f32 v[24:25], v[24:25], v[64:65] op_sel_hi:[1,0]
	s_waitcnt lgkmcnt(0)
	s_nop 0
	v_mfma_f32_16x16x32_bf16 v[24:27], v[106:109], v[102:105], v[24:27]
	v_add_f32_e32 v102, 0, v116
	v_add_f32_e32 v102, v110, v102
	v_add_f32_e32 v102, v112, v102
	v_add_f32_e32 v114, v111, v102
	ds_read_b128 v[102:105], v76 offset:128
	ds_read_b128 v[106:109], v76 offset:144
	ds_read_b128 v[110:113], v62 offset:4160
	s_waitcnt lgkmcnt(0)
	v_lshlrev_b32_e32 v115, 16, v110
	v_and_b32_e32 v110, 0xffff0000, v110
	v_lshlrev_b32_e32 v116, 16, v111
	v_and_b32_e32 v111, 0xffff0000, v111
	v_lshlrev_b32_e32 v117, 16, v112
	v_and_b32_e32 v112, 0xffff0000, v112
	v_lshlrev_b32_e32 v118, 16, v113
	v_and_b32_e32 v113, 0xffff0000, v113
	v_mul_f32_e32 v102, v102, v115
	v_mul_f32_e32 v103, v103, v110
	v_mul_f32_e32 v104, v104, v116
	v_mul_f32_e32 v115, v106, v117
	v_fma_f32 v117, v106, v117, v102
	v_mul_f32_e32 v106, v107, v112
	v_fma_f32 v110, v107, v112, v103
	v_mul_f32_e32 v107, v108, v118
	v_fma_f32 v112, v108, v118, v104
	v_mul_f32_e32 v105, v105, v111
	v_mul_f32_e32 v108, v109, v113
	v_fma_f32 v111, v109, v113, v105
	v_cvt_pk_bf16_f32 v102, v102, v103
	v_cvt_pk_bf16_f32 v103, v104, v105
	v_cvt_pk_bf16_f32 v104, v115, v106
	v_cvt_pk_bf16_f32 v105, v107, v108
	ds_read_b128 v[106:109], v61 offset:38976
	s_waitcnt lgkmcnt(0)
	v_mfma_f32_16x16x32_bf16 v[20:23], v[106:109], v[102:105], v[20:23]
	ds_read_b128 v[106:109], v61 offset:43328
	s_waitcnt lgkmcnt(0)
	v_mfma_f32_16x16x32_bf16 v[24:27], v[106:109], v[102:105], v[24:27]
	v_add_f32_e32 v102, v114, v117
	v_add_f32_e32 v102, v110, v102
	v_add_f32_e32 v102, v112, v102
	v_add_f32_e32 v114, v111, v102
	ds_read_b128 v[102:105], v76 offset:256
	ds_read_b128 v[106:109], v76 offset:272
	ds_read_b128 v[110:113], v62 offset:4224
	s_waitcnt lgkmcnt(0)
	v_lshlrev_b32_e32 v115, 16, v110
	v_and_b32_e32 v110, 0xffff0000, v110
	v_lshlrev_b32_e32 v116, 16, v111
	v_and_b32_e32 v111, 0xffff0000, v111
	v_lshlrev_b32_e32 v117, 16, v112
	v_and_b32_e32 v112, 0xffff0000, v112
	v_lshlrev_b32_e32 v118, 16, v113
	v_and_b32_e32 v113, 0xffff0000, v113
	v_mul_f32_e32 v102, v102, v115
	v_mul_f32_e32 v103, v103, v110
	v_mul_f32_e32 v104, v104, v116
	v_mul_f32_e32 v115, v106, v117
	v_fma_f32 v117, v106, v117, v102
	v_mul_f32_e32 v106, v107, v112
	v_fma_f32 v110, v107, v112, v103
	v_mul_f32_e32 v107, v108, v118
	v_fma_f32 v112, v108, v118, v104
	v_mul_f32_e32 v105, v105, v111
	v_mul_f32_e32 v108, v109, v113
	v_fma_f32 v111, v109, v113, v105
	v_cvt_pk_bf16_f32 v102, v102, v103
	v_cvt_pk_bf16_f32 v103, v104, v105
	v_cvt_pk_bf16_f32 v104, v115, v106
	v_cvt_pk_bf16_f32 v105, v107, v108
	ds_read_b128 v[106:109], v61 offset:39040
	s_waitcnt lgkmcnt(0)
	v_mfma_f32_16x16x32_bf16 v[20:23], v[106:109], v[102:105], v[20:23]
	ds_read_b128 v[106:109], v61 offset:43392
	s_waitcnt lgkmcnt(0)
	v_mfma_f32_16x16x32_bf16 v[24:27], v[106:109], v[102:105], v[24:27]
	v_add_f32_e32 v102, v114, v117
	v_add_f32_e32 v102, v110, v102
	v_add_f32_e32 v102, v112, v102
	v_add_f32_e32 v114, v111, v102
	ds_read_b128 v[102:105], v76 offset:384
	ds_read_b128 v[106:109], v76 offset:400
	ds_read_b128 v[110:113], v62 offset:4288
	s_waitcnt lgkmcnt(0)
	v_lshlrev_b32_e32 v62, 16, v110
	v_and_b32_e32 v110, 0xffff0000, v110
	v_lshlrev_b32_e32 v115, 16, v111
	v_and_b32_e32 v111, 0xffff0000, v111
	v_lshlrev_b32_e32 v116, 16, v112
	v_and_b32_e32 v112, 0xffff0000, v112
	v_lshlrev_b32_e32 v117, 16, v113
	v_and_b32_e32 v113, 0xffff0000, v113
	v_mul_f32_e32 v62, v102, v62
	v_mul_f32_e32 v102, v103, v110
	v_mul_f32_e32 v118, v106, v116
	v_fma_f32 v116, v106, v116, v62
	v_mul_f32_e32 v106, v107, v112
	v_fma_f32 v110, v107, v112, v102
	v_mul_f32_e32 v103, v104, v115
	v_mul_f32_e32 v107, v108, v117
	v_mul_f32_e32 v104, v105, v111
	v_mul_f32_e32 v105, v109, v113
	v_fma_f32 v112, v108, v117, v103
	v_fma_f32 v111, v109, v113, v104
	v_cvt_pk_bf16_f32 v102, v62, v102
	v_cvt_pk_bf16_f32 v103, v103, v104
	v_cvt_pk_bf16_f32 v104, v118, v106
	v_cvt_pk_bf16_f32 v105, v107, v105
	ds_read_b128 v[106:109], v61 offset:39104
	s_waitcnt lgkmcnt(0)
	v_mfma_f32_16x16x32_bf16 v[20:23], v[106:109], v[102:105], v[20:23]
	ds_read_b128 v[106:109], v61 offset:43456
	v_add_f32_e32 v61, v114, v116
	v_add_f32_e32 v61, v110, v61
	v_add_f32_e32 v61, v112, v61
	v_add_f32_e32 v61, v111, v61
	ds_bpermute_b32 v62, v98, v61
	s_waitcnt lgkmcnt(1)
	v_mfma_f32_16x16x32_bf16 v[24:27], v[106:109], v[102:105], v[24:27]
	s_waitcnt lgkmcnt(0)
	v_add_f32_e32 v61, v61, v62
	ds_bpermute_b32 v62, v99, v61
	s_andn2_b64 vcc, exec, s[40:41]
	s_cbranch_vccnz .LBB0_446
	s_bitcmp1_b32 s24, 0
	s_cselect_b32 s40, 0xae00, 0
	s_add_i32 s42, s40, 0
	v_add_u32_e32 v102, s42, v73
	v_add_u32_e32 v103, s42, v81
	s_bitcmp1_b32 s24, 0
	s_cbranch_scc0 .Lmls_stA
	s_cmp_lg_u64 s[34:35], 0
	s_cbranch_scc0 .Lmls_genB
	s_cmp_eq_u32 s24, 1
	s_cbranch_scc1 .Lmls_w0aB
	s_cmp_eq_u32 s24, 33
	s_cbranch_scc1 .Lmls_w0cB
	s_waitcnt vmcnt(41)
	ds_write_b128 v102, v[120:123] offset:4096
	s_waitcnt vmcnt(40)
	ds_write_b128 v103, v[124:127] offset:4096
	v_add_u32_e32 v103, s42, v82
	s_waitcnt vmcnt(39)
	ds_write_b128 v103, v[128:131] offset:4096
	v_add_u32_e32 v103, s42, v83
	s_waitcnt vmcnt(38)
	ds_write_b128 v103, v[132:135] offset:4096
	s_waitcnt vmcnt(37)
	ds_write_b128 v102, v[136:139] offset:38912
	s_branch .Lmls_ldB
.Lmls_w0aB:
	s_waitcnt vmcnt(25)
	ds_write_b128 v102, v[120:123] offset:4096
	s_waitcnt vmcnt(24)
	ds_write_b128 v103, v[124:127] offset:4096
	v_add_u32_e32 v103, s42, v82
	s_waitcnt vmcnt(23)
	ds_write_b128 v103, v[128:131] offset:4096
	v_add_u32_e32 v103, s42, v83
	s_waitcnt vmcnt(22)
	ds_write_b128 v103, v[132:135] offset:4096
	s_waitcnt vmcnt(21)
	ds_write_b128 v102, v[136:139] offset:38912
	s_branch .Lmls_ldB
.Lmls_w0cB:
	s_waitcnt vmcnt(36)
	ds_write_b128 v102, v[120:123] offset:4096
	s_waitcnt vmcnt(35)
	ds_write_b128 v103, v[124:127] offset:4096
	v_add_u32_e32 v103, s42, v82
	s_waitcnt vmcnt(34)
	ds_write_b128 v103, v[128:131] offset:4096
	v_add_u32_e32 v103, s42, v83
	s_waitcnt vmcnt(33)
	ds_write_b128 v103, v[132:135] offset:4096
	s_waitcnt vmcnt(32)
	ds_write_b128 v102, v[136:139] offset:38912
	s_branch .Lmls_ldB
.Lmls_genB:
	s_waitcnt vmcnt(17)
	ds_write_b128 v102, v[120:123] offset:4096
	s_waitcnt vmcnt(16)
	ds_write_b128 v103, v[124:127] offset:4096
	v_add_u32_e32 v103, s42, v82
	s_waitcnt vmcnt(15)
	ds_write_b128 v103, v[128:131] offset:4096
	v_add_u32_e32 v103, s42, v83
	s_waitcnt vmcnt(14)
	ds_write_b128 v103, v[132:135] offset:4096
	s_waitcnt vmcnt(13)
	ds_write_b128 v102, v[136:139] offset:38912
.Lmls_ldB:
	s_and_saveexec_b64 s[40:41], s[2:3]
	s_cbranch_execz .LBB0_445
	v_lshl_add_u32 v102, v29, 2, s42
	ds_write_b32 v102, v140 offset:47616
	s_branch .LBB0_445
.Lmls_stA:
	s_cmp_lg_u64 s[34:35], 0
	s_cbranch_scc0 .Lmls_genA
	s_cmp_eq_u32 s24, 1
	s_cbranch_scc1 .Lmls_w0aA
	s_cmp_eq_u32 s24, 33
	s_cbranch_scc1 .Lmls_w0cA
	s_waitcnt vmcnt(41)
	ds_write_b128 v102, v[0:3] offset:4096
	s_waitcnt vmcnt(40)
	ds_write_b128 v103, v[4:7] offset:4096
	v_add_u32_e32 v103, s42, v82
	s_waitcnt vmcnt(39)
	ds_write_b128 v103, v[8:11] offset:4096
	v_add_u32_e32 v103, s42, v83
	s_waitcnt vmcnt(38)
	ds_write_b128 v103, v[12:15] offset:4096
	s_waitcnt vmcnt(37)
	ds_write_b128 v102, v[16:19] offset:38912
	s_branch .Lmls_ldA
.Lmls_w0aA:
	s_waitcnt vmcnt(25)
	ds_write_b128 v102, v[0:3] offset:4096
	s_waitcnt vmcnt(24)
	ds_write_b128 v103, v[4:7] offset:4096
	v_add_u32_e32 v103, s42, v82
	s_waitcnt vmcnt(23)
	ds_write_b128 v103, v[8:11] offset:4096
	v_add_u32_e32 v103, s42, v83
	s_waitcnt vmcnt(22)
	ds_write_b128 v103, v[12:15] offset:4096
	s_waitcnt vmcnt(21)
	ds_write_b128 v102, v[16:19] offset:38912
	s_branch .Lmls_ldA
.Lmls_w0cA:
	s_waitcnt vmcnt(36)
	ds_write_b128 v102, v[0:3] offset:4096
	s_waitcnt vmcnt(35)
	ds_write_b128 v103, v[4:7] offset:4096
	v_add_u32_e32 v103, s42, v82
	s_waitcnt vmcnt(34)
	ds_write_b128 v103, v[8:11] offset:4096
	v_add_u32_e32 v103, s42, v83
	s_waitcnt vmcnt(33)
	ds_write_b128 v103, v[12:15] offset:4096
	s_waitcnt vmcnt(32)
	ds_write_b128 v102, v[16:19] offset:38912
	s_branch .Lmls_ldA
.Lmls_genA:
	s_waitcnt vmcnt(17)
	ds_write_b128 v102, v[0:3] offset:4096
	s_waitcnt vmcnt(16)
	ds_write_b128 v103, v[4:7] offset:4096
	v_add_u32_e32 v103, s42, v82
	s_waitcnt vmcnt(15)
	ds_write_b128 v103, v[8:11] offset:4096
	v_add_u32_e32 v103, s42, v83
	s_waitcnt vmcnt(14)
	ds_write_b128 v103, v[12:15] offset:4096
	s_waitcnt vmcnt(13)
	ds_write_b128 v102, v[16:19] offset:38912
.Lmls_ldA:
	s_and_saveexec_b64 s[40:41], s[2:3]
	s_cbranch_execz .LBB0_445
	v_lshl_add_u32 v102, v29, 2, s42
	ds_write_b32 v102, v88 offset:47616
	s_branch .LBB0_445
